# seam 4: L2 write-back skipped when every blockIdx-mod-8 class sits on one XCC (phase 4 outputs are read through the same L2); flag words raised in the prologue
# baseline (speedup 1.0000x reference)
; __device__ __forceinline__ void p0_prologue(const Ptrs& P, LAS unsigned char* lds, int gw, int NGW, int wave, int lane, int gtid, int GT, int part) {
;     ...
;     float* ssq0 = (float*)(P.ws + WS_SSQ0); float* ssq1 = (float*)(P.ws + WS_SSQ1); float* ssq2 = (float*)(P.ws + WS_SSQ2);
;     for (int g = gtid; g < M; g += GT) { ssq1[g] = 0.0f; ssq2[g] = 0.0f; }
;     { unsigned long long* XS = (unsigned long long*)(P.ws + WS_X); for (int g = gtid; g < M * 4 + 1024; g += GT) XS[g] = 0ull; }
;     { unsigned long long* GR = (unsigned long long*)(P.ws + WS_SUM); for (int g = gtid; g < 64 * NCHUNK * LB; g += GT) GR[g] = 0ull; }
.Lp0_skip_tables:
	s_mov_b64 s[2:3], exec
	s_mov_b64 exec, s[0:1]
	s_and_b32 s4, s33, 7
	s_lshl_b32 s4, s4, 2
	s_add_i32 s4, s4, 0x3700
	v_mov_b32_e32 v177, s4
	s_lshl_b32 s5, 1, s59
	s_cmpk_eq_i32 s64, 0x100
	s_cselect_b32 s5, s5, 0xff
	v_mov_b32_e32 v178, s5
	global_atomic_or v177, v178, s[54:55]
	s_mov_b64 exec, s[2:3]
	v_lshlrev_b32_e32 v177, 3, v232
	v_mov_b32_e32 v178, 0
	v_mov_b32_e32 v179, 0
	s_lshl_b32 s2, s60, 9
	s_lshl_b32 s3, s62, 9

; __device__ __forceinline__ unsigned xb_add(unsigned* p, unsigned v) { return __hip_atomic_fetch_add(p, v, __ATOMIC_RELAXED, __HIP_MEMORY_SCOPE_AGENT); }
; __device__ __forceinline__ void xcd_barrier(const XcdBarrier& b) {
;     ...
;     if (threadIdx.x == 0) {
;         unsigned* bar = b.bar;
;         __builtin_amdgcn_s_waitcnt(0);
;         unsigned nloc = b.st[0], nx = b.st[1];
;         if (nloc == 0u) { xcd_barrier_complete(bar, b.x, nloc, nx); b.st[0] = nloc; b.st[1] = nx; }
;         const unsigned old = xb_add(&bar[XB_XSUB(b.x)], 1u);
;         const unsigned gen = old / nloc;
;         if (old + 1u == (gen + 1u) * nloc) {
;             __builtin_amdgcn_fence(__ATOMIC_RELEASE, "agent");
;             asm volatile("s_waitcnt vmcnt(0)" ::: "memory");
;             const unsigned og = xb_add(&bar[XB_TOP], 1u);
.LBB0_441:
	s_waitcnt lgkmcnt(0)
	v_readfirstlane_b32 s98, v2
	v_readfirstlane_b32 s99, v0
	v_mov_b32_e32 v1, 0x20008
	ds_read_b32 v5, v1
	s_lshl_b32 s96, s59, 8
	s_add_u32 s96, s54, s96
	s_addc_u32 s97, s55, 0
	v_mov_b32_e32 v3, 0x1000
	v_mov_b32_e32 v4, 1
	v_mov_b32_e32 v6, 0x3700
	global_load_dwordx4 v[8:11], v6, s[54:55] sc1
	global_load_dwordx4 v[12:15], v6, s[54:55] offset:16 sc1
	global_atomic_add v3, v3, v4, s[96:97] offset:1024 sc0
	s_waitcnt lgkmcnt(0)
	v_readfirstlane_b32 s100, v5
	s_add_i32 s100, s100, 1
	v_mov_b32_e32 v2, s100
	ds_write_b32 v1, v2
	s_mul_i32 s98, s98, s100
	s_mul_i32 s99, s99, s100
	s_waitcnt vmcnt(0)
	v_readfirstlane_b32 s96, v3
	v_add_u32_e32 v16, -1, v8
	v_and_b32_e32 v8, v16, v8
	v_add_u32_e32 v16, -1, v9
	v_and_b32_e32 v9, v16, v9
	v_add_u32_e32 v16, -1, v10
	v_and_b32_e32 v10, v16, v10
	v_add_u32_e32 v16, -1, v11
	v_and_b32_e32 v11, v16, v11
	v_add_u32_e32 v16, -1, v12
	v_and_b32_e32 v12, v16, v12
	v_add_u32_e32 v16, -1, v13
	v_and_b32_e32 v13, v16, v13
	v_add_u32_e32 v16, -1, v14
	v_and_b32_e32 v14, v16, v14
	v_add_u32_e32 v16, -1, v15
	v_and_b32_e32 v15, v16, v15
	v_or3_b32 v8, v8, v9, v10
	v_or3_b32 v11, v11, v12, v13
	v_or3_b32 v8, v8, v14, v15
	v_or_b32_e32 v8, v8, v11
	v_readfirstlane_b32 s97, v8
	s_add_i32 s96, s96, 1
	s_cmp_lg_u32 s96, s98
	s_cbranch_scc1 .Lmy_bar_poll_3
	s_cmp_eq_u32 s97, 0
	s_cbranch_scc1 .Lmy_bar_nowb_3
	buffer_wbl2 sc1
	s_waitcnt vmcnt(0)
.Lmy_bar_nowb_3:
	v_mov_b32_e32 v3, 0x3000
	global_atomic_add v3, v4, s[54:55] offset:1024
